# v38 + non-temporal loads for the final norm's read-once bf16 rows (probe: -8.6 us for the phase)
# baseline (speedup 1.0000x reference)
.LBB0_300:
	v_add_co_u32_e32 v0, vcc, 0xfffff000, v20
	s_movk_i32 s1, 0xd000
	s_nop 0
	v_addc_co_u32_e32 v1, vcc, -1, v21, vcc
	global_load_dwordx4 v[22:25], v[0:1], off offset:-3072 nt
	global_load_dwordx4 v[26:29], v[0:1], off offset:-2048 nt
	global_load_dwordx4 v[30:33], v[0:1], off offset:-1024 nt
	global_load_dwordx4 v[84:87], v[20:21], off offset:-4096 nt
	global_load_dwordx4 v[34:37], v[20:21], off offset:-3072 nt
	global_load_dwordx4 v[12:15], v[20:21], off offset:-2048 nt
	global_load_dwordx4 v[62:65], v[20:21], off offset:-1024 nt
	global_load_dwordx4 v[8:11], v[20:21], off nt
	global_load_dwordx4 v[0:3], v[16:17], off offset:16
	global_load_dwordx4 v[4:7], v[16:17], off
	s_add_i32 s0, s0, s30
	v_lshl_add_u64 v[20:21], v[20:21], 0, s[70:71]
	s_cmp_gt_i32 s0, 0xbfff
	s_waitcnt vmcnt(9)
	v_and_b32_e32 v47, 0xffff0000, v22
	v_lshlrev_b32_e32 v46, 16, v22
	s_waitcnt vmcnt(7)
	v_and_b32_e32 v49, 0xffff0000, v30
	v_lshlrev_b32_e32 v44, 16, v24
	v_and_b32_e32 v45, 0xffff0000, v24
	v_lshlrev_b32_e32 v42, 16, v25
	v_and_b32_e32 v43, 0xffff0000, v25
	v_lshlrev_b32_e32 v48, 16, v30
	v_mov_b32_e32 v24, v49
	v_mov_b32_e32 v25, v47
	v_lshlrev_b32_e32 v40, 16, v23
	v_and_b32_e32 v41, 0xffff0000, v23
	v_mov_b32_e32 v22, v48
	v_mov_b32_e32 v23, v46
	v_pk_mul_f32 v[24:25], v[24:25], v[24:25]
	s_waitcnt vmcnt(5)
	v_and_b32_e32 v73, 0xffff0000, v34
	v_lshlrev_b32_e32 v70, 16, v35
	v_and_b32_e32 v71, 0xffff0000, v35
	s_waitcnt vmcnt(3)
	v_and_b32_e32 v35, 0xffff0000, v62
	v_pk_fma_f32 v[38:39], v[22:23], v[22:23], v[24:25]
	v_lshlrev_b32_e32 v56, 16, v31
	v_lshlrev_b32_e32 v72, 16, v34
	v_lshlrev_b32_e32 v34, 16, v62
	v_mov_b32_e32 v24, v35
	v_mov_b32_e32 v25, v73
	v_and_b32_e32 v57, 0xffff0000, v31
	v_mov_b32_e32 v76, v56
	v_mov_b32_e32 v77, v40
	v_mov_b32_e32 v22, v34
	v_mov_b32_e32 v23, v72
	v_pk_mul_f32 v[24:25], v[24:25], v[24:25]
	v_lshlrev_b32_e32 v52, 16, v32
	v_and_b32_e32 v53, 0xffff0000, v32
	v_lshlrev_b32_e32 v50, 16, v33
	v_and_b32_e32 v51, 0xffff0000, v33
	v_pk_fma_f32 v[60:61], v[22:23], v[22:23], v[24:25]
	v_lshlrev_b32_e32 v32, 16, v64
	v_and_b32_e32 v33, 0xffff0000, v64
	v_lshlrev_b32_e32 v30, 16, v65
	v_and_b32_e32 v31, 0xffff0000, v65
	v_lshlrev_b32_e32 v64, 16, v26
	v_and_b32_e32 v65, 0xffff0000, v26
	v_lshlrev_b32_e32 v74, 16, v27
	v_and_b32_e32 v75, 0xffff0000, v27
	v_lshlrev_b32_e32 v22, 16, v28
	v_and_b32_e32 v23, 0xffff0000, v28
	v_lshlrev_b32_e32 v26, 16, v29
	v_and_b32_e32 v27, 0xffff0000, v29
	v_mov_b32_e32 v28, v57
	v_mov_b32_e32 v29, v41
	v_pk_fma_f32 v[38:39], v[76:77], v[76:77], v[38:39]
	v_mov_b32_e32 v76, v53
	v_pk_fma_f32 v[28:29], v[28:29], v[28:29], v[38:39]
	v_mov_b32_e32 v38, v52
	v_mov_b32_e32 v39, v44
	v_mov_b32_e32 v77, v45
	v_pk_fma_f32 v[28:29], v[38:39], v[38:39], v[28:29]
	v_mov_b32_e32 v38, v50
	v_pk_fma_f32 v[28:29], v[76:77], v[76:77], v[28:29]
	v_mov_b32_e32 v39, v42
	v_lshlrev_b32_e32 v54, 16, v84
	v_mov_b32_e32 v76, v51
	v_mov_b32_e32 v77, v43
	v_pk_fma_f32 v[28:29], v[38:39], v[38:39], v[28:29]
	v_and_b32_e32 v55, 0xffff0000, v84
	v_pk_fma_f32 v[28:29], v[76:77], v[76:77], v[28:29]
	v_mov_b32_e32 v38, v54
	v_mov_b32_e32 v39, v64
	v_lshlrev_b32_e32 v58, 16, v85
	v_mov_b32_e32 v76, v55
	v_mov_b32_e32 v77, v65
	v_pk_fma_f32 v[28:29], v[38:39], v[38:39], v[28:29]
	v_and_b32_e32 v59, 0xffff0000, v85
	v_lshlrev_b32_e32 v24, 16, v86
	v_and_b32_e32 v25, 0xffff0000, v86
	v_pk_fma_f32 v[28:29], v[76:77], v[76:77], v[28:29]
	v_mov_b32_e32 v38, v58
	v_mov_b32_e32 v39, v74
	v_pk_mul_f32 v[88:89], v[22:23], v[22:23]
	v_pk_mul_f32 v[84:85], v[24:25], v[24:25]
	v_mov_b32_e32 v76, v59
	v_mov_b32_e32 v77, v75
	v_pk_fma_f32 v[28:29], v[38:39], v[38:39], v[28:29]
	v_mov_b32_e32 v38, v84
	v_pk_fma_f32 v[28:29], v[76:77], v[76:77], v[28:29]
	v_mov_b32_e32 v39, v88
	v_pk_add_f32 v[38:39], v[38:39], v[28:29]
	v_lshlrev_b32_e32 v28, 16, v87
	v_and_b32_e32 v29, 0xffff0000, v87
	v_pk_mul_f32 v[90:91], v[26:27], v[26:27]
	v_pk_mul_f32 v[76:77], v[28:29], v[28:29]
	v_mov_b32_e32 v88, v85
	v_pk_add_f32 v[38:39], v[88:89], v[38:39]
	v_mov_b32_e32 v84, v76
	v_mov_b32_e32 v85, v90
	v_pk_add_f32 v[38:39], v[84:85], v[38:39]
	v_mov_b32_e32 v90, v77
	v_pk_add_f32 v[38:39], v[90:91], v[38:39]
	ds_bpermute_b32 v77, v78, v39
	ds_bpermute_b32 v76, v78, v38
	v_mov_b64_e32 v[88:89], s[68:69]
	v_lshlrev_b32_e32 v68, 16, v36
	v_and_b32_e32 v69, 0xffff0000, v36
	v_lshlrev_b32_e32 v36, 16, v63
	s_waitcnt lgkmcnt(0)
	v_pk_add_f32 v[38:39], v[38:39], v[76:77]
	ds_bpermute_b32 v77, v79, v39
	ds_bpermute_b32 v76, v79, v38
	v_lshlrev_b32_e32 v66, 16, v37
	v_and_b32_e32 v67, 0xffff0000, v37
	v_and_b32_e32 v37, 0xffff0000, v63
	v_mov_b32_e32 v62, v36
	s_waitcnt lgkmcnt(0)
	v_pk_add_f32 v[38:39], v[38:39], v[76:77]
	ds_bpermute_b32 v77, v80, v39
	ds_bpermute_b32 v76, v80, v38
	v_mov_b32_e32 v63, v70
	v_pk_fma_f32 v[60:61], v[62:63], v[62:63], v[60:61]
	v_mov_b32_e32 v62, v32
	v_mov_b32_e32 v63, v68
	s_waitcnt lgkmcnt(0)
	v_pk_add_f32 v[38:39], v[38:39], v[76:77]
	ds_bpermute_b32 v77, v81, v39
	ds_bpermute_b32 v76, v81, v38
	s_waitcnt lgkmcnt(0)
	v_pk_add_f32 v[38:39], v[38:39], v[76:77]
	ds_bpermute_b32 v77, v82, v39
	ds_bpermute_b32 v76, v82, v38
	s_waitcnt lgkmcnt(0)
	v_pk_add_f32 v[38:39], v[38:39], v[76:77]
	ds_bpermute_b32 v77, v83, v39
	ds_bpermute_b32 v76, v83, v38
	s_waitcnt lgkmcnt(0)
	v_pk_add_f32 v[38:39], v[38:39], v[76:77]
	s_nop 0
	v_pk_fma_f32 v[76:77], v[38:39], s[74:75], v[88:89] op_sel_hi:[1,0,0]
	s_nop 0
	v_mul_f32_e32 v38, 0x4b800000, v77
	v_cmp_gt_f32_e64 s[40:41], s19, v77
	v_cmp_gt_f32_e32 vcc, s19, v76
	s_nop 0
	v_cndmask_b32_e64 v38, v77, v38, s[40:41]
	v_rsq_f32_e32 v38, v38
	s_nop 0
	v_mul_f32_e32 v39, 0x45800000, v38
	v_cndmask_b32_e64 v38, v38, v39, s[40:41]
	v_pk_mul_f32 v[40:41], v[38:39], v[40:41] op_sel_hi:[0,1]
	v_pk_mul_f32 v[46:47], v[38:39], v[46:47] op_sel_hi:[0,1]
	s_waitcnt vmcnt(0)
	v_pk_mul_f32 v[86:87], v[6:7], v[40:41]
	v_add_co_u32_e64 v40, s[40:41], s1, v18
	v_pk_mul_f32 v[44:45], v[38:39], v[44:45] op_sel_hi:[0,1]
	v_pk_mul_f32 v[42:43], v[38:39], v[42:43] op_sel_hi:[0,1]
	v_pk_mul_f32 v[84:85], v[4:5], v[46:47]
	v_addc_co_u32_e64 v41, s[40:41], -1, v19, s[40:41]
	v_pk_mul_f32 v[44:45], v[0:1], v[44:45]
	v_pk_mul_f32 v[46:47], v[2:3], v[42:43]
	global_store_dwordx4 v[40:41], v[44:47], off offset:-2048
	global_store_dwordx4 v[40:41], v[84:87], off offset:-2064
	s_movk_i32 s1, 0xe000
	v_pk_mul_f32 v[44:45], v[38:39], v[64:65] op_sel_hi:[0,1]
	v_pk_mul_f32 v[46:47], v[38:39], v[74:75] op_sel_hi:[0,1]
	v_mul_f32_e32 v39, 0x4b800000, v76
	v_cndmask_b32_e32 v39, v76, v39, vcc
	v_rsq_f32_e32 v39, v39
	v_mov_b32_e32 v86, v37
	v_mov_b32_e32 v87, v71
	v_pk_fma_f32 v[60:61], v[86:87], v[86:87], v[60:61]
	v_mul_f32_e32 v42, 0x45800000, v39
	v_cndmask_b32_e32 v42, v39, v42, vcc
	v_pk_mul_f32 v[48:49], v[42:43], v[48:49] op_sel_hi:[0,1]
	v_pk_mul_f32 v[74:75], v[4:5], v[48:49]
	v_pk_mul_f32 v[48:49], v[42:43], v[56:57] op_sel_hi:[0,1]
	v_pk_mul_f32 v[76:77], v[6:7], v[48:49]
	v_add_co_u32_e32 v48, vcc, s1, v18
	v_pk_mul_f32 v[52:53], v[42:43], v[52:53] op_sel_hi:[0,1]
	s_nop 0
	v_addc_co_u32_e32 v49, vcc, -1, v19, vcc
	v_pk_mul_f32 v[50:51], v[42:43], v[50:51] op_sel_hi:[0,1]
	v_mov_b32_e32 v86, v33
	v_mov_b32_e32 v87, v69
	v_pk_fma_f32 v[60:61], v[62:63], v[62:63], v[60:61]
	global_store_dwordx4 v[48:49], v[74:77], off offset:-2064
	v_pk_fma_f32 v[60:61], v[86:87], v[86:87], v[60:61]
	v_mov_b32_e32 v62, v30
	v_pk_mul_f32 v[74:75], v[0:1], v[52:53]
	v_pk_mul_f32 v[76:77], v[2:3], v[50:51]
	v_mov_b32_e32 v63, v66
	global_store_dwordx4 v[48:49], v[74:77], off offset:-2048
	v_lshlrev_b32_e32 v52, 16, v8
	v_mov_b32_e32 v86, v31
	v_lshlrev_b32_e32 v74, 16, v12
	v_mov_b32_e32 v87, v67
	v_pk_fma_f32 v[60:61], v[62:63], v[62:63], v[60:61]
	v_and_b32_e32 v75, 0xffff0000, v12
	v_and_b32_e32 v53, 0xffff0000, v8
	v_pk_fma_f32 v[60:61], v[86:87], v[86:87], v[60:61]
	v_mov_b32_e32 v62, v52
	v_mov_b32_e32 v63, v74
	v_lshlrev_b32_e32 v76, 16, v13
	v_lshlrev_b32_e32 v50, 16, v14
	v_and_b32_e32 v51, 0xffff0000, v14
	v_lshlrev_b32_e32 v14, 16, v9
	v_mov_b32_e32 v86, v53
	v_mov_b32_e32 v87, v75
	v_pk_fma_f32 v[60:61], v[62:63], v[62:63], v[60:61]
	v_pk_mul_f32 v[56:57], v[42:43], v[54:55] op_sel_hi:[0,1]
	v_and_b32_e32 v77, 0xffff0000, v13
	v_lshlrev_b32_e32 v54, 16, v15
	v_and_b32_e32 v55, 0xffff0000, v15
	v_and_b32_e32 v15, 0xffff0000, v9
	v_lshlrev_b32_e32 v12, 16, v10
	v_and_b32_e32 v13, 0xffff0000, v10
	v_pk_fma_f32 v[60:61], v[86:87], v[86:87], v[60:61]
	v_mov_b32_e32 v62, v14
	v_mov_b32_e32 v63, v76
	v_pk_mul_f32 v[64:65], v[50:51], v[50:51]
	v_pk_mul_f32 v[8:9], v[12:13], v[12:13]
	v_mov_b32_e32 v86, v15
	v_mov_b32_e32 v87, v77
	v_pk_fma_f32 v[60:61], v[62:63], v[62:63], v[60:61]
	v_mov_b32_e32 v62, v8
	v_pk_fma_f32 v[60:61], v[86:87], v[86:87], v[60:61]
	v_mov_b32_e32 v63, v64
	v_pk_add_f32 v[62:63], v[62:63], v[60:61]
	v_lshlrev_b32_e32 v60, 16, v11
	v_and_b32_e32 v61, 0xffff0000, v11
	v_pk_mul_f32 v[84:85], v[54:55], v[54:55]
	v_pk_mul_f32 v[10:11], v[60:61], v[60:61]
	v_mov_b32_e32 v64, v9
	v_pk_add_f32 v[8:9], v[64:65], v[62:63]
	v_mov_b32_e32 v62, v10
	v_mov_b32_e32 v63, v84
	v_pk_add_f32 v[8:9], v[62:63], v[8:9]
	v_mov_b32_e32 v84, v11
	v_pk_add_f32 v[8:9], v[84:85], v[8:9]
	ds_bpermute_b32 v11, v78, v9
	ds_bpermute_b32 v10, v78, v8
	v_pk_mul_f32 v[58:59], v[42:43], v[58:59] op_sel_hi:[0,1]
	s_movk_i32 s1, 0xf000
	s_waitcnt lgkmcnt(0)
	v_pk_add_f32 v[8:9], v[8:9], v[10:11]
	ds_bpermute_b32 v11, v79, v9
	ds_bpermute_b32 v10, v79, v8
	s_waitcnt lgkmcnt(0)
	v_pk_add_f32 v[8:9], v[8:9], v[10:11]
	ds_bpermute_b32 v11, v80, v9
	ds_bpermute_b32 v10, v80, v8
	s_waitcnt lgkmcnt(0)
	v_pk_add_f32 v[8:9], v[8:9], v[10:11]
	ds_bpermute_b32 v11, v81, v9
	ds_bpermute_b32 v10, v81, v8
	s_waitcnt lgkmcnt(0)
	v_pk_add_f32 v[8:9], v[8:9], v[10:11]
	ds_bpermute_b32 v11, v82, v9
	ds_bpermute_b32 v10, v82, v8
	s_waitcnt lgkmcnt(0)
	v_pk_add_f32 v[8:9], v[8:9], v[10:11]
	ds_bpermute_b32 v11, v83, v9
	ds_bpermute_b32 v10, v83, v8
	s_waitcnt lgkmcnt(0)
	v_pk_add_f32 v[8:9], v[8:9], v[10:11]
	s_nop 0
	v_pk_fma_f32 v[64:65], v[8:9], s[74:75], v[88:89] op_sel_hi:[1,0,0]
	s_nop 0
	v_mul_f32_e32 v8, 0x4b800000, v65
	v_cmp_gt_f32_e32 vcc, s19, v64
	v_cmp_gt_f32_e64 s[40:41], s19, v65
	v_mul_f32_e32 v39, 0x4b800000, v64
	v_cndmask_b32_e32 v39, v64, v39, vcc
	v_cndmask_b32_e64 v8, v65, v8, s[40:41]
	v_rsq_f32_e32 v8, v8
	v_rsq_f32_e32 v39, v39
	v_mul_f32_e32 v9, 0x45800000, v8
	v_mul_f32_e32 v43, 0x45800000, v39
	v_cndmask_b32_e64 v62, v8, v9, s[40:41]
	v_cndmask_b32_e32 v64, v39, v43, vcc
	v_pk_mul_f32 v[8:9], v[62:63], v[72:73] op_sel_hi:[0,1]
	v_pk_mul_f32 v[34:35], v[64:65], v[34:35] op_sel_hi:[0,1]
	v_pk_mul_f32 v[8:9], v[4:5], v[8:9]
	v_pk_mul_f32 v[10:11], v[62:63], v[70:71] op_sel_hi:[0,1]
	v_add_co_u32_e64 v70, s[40:41], s1, v18
	v_pk_mul_f32 v[4:5], v[4:5], v[34:35]
	v_pk_mul_f32 v[34:35], v[64:65], v[36:37] op_sel_hi:[0,1]
	v_pk_mul_f32 v[10:11], v[6:7], v[10:11]
	v_addc_co_u32_e64 v71, s[40:41], -1, v19, s[40:41]
	v_pk_mul_f32 v[6:7], v[6:7], v[34:35]
	global_store_dwordx4 v[70:71], v[8:11], off offset:-2064
	global_store_dwordx4 v[18:19], v[4:7], off offset:-2064
	v_pk_mul_f32 v[26:27], v[38:39], v[26:27] op_sel_hi:[0,1]
	v_pk_mul_f32 v[8:9], v[62:63], v[68:69] op_sel_hi:[0,1]
	v_pk_mul_f32 v[4:5], v[64:65], v[32:33] op_sel_hi:[0,1]
	v_pk_mul_f32 v[8:9], v[0:1], v[8:9]
	v_pk_mul_f32 v[10:11], v[62:63], v[66:67] op_sel_hi:[0,1]
	v_pk_mul_f32 v[0:1], v[0:1], v[4:5]
	v_pk_mul_f32 v[4:5], v[64:65], v[30:31] op_sel_hi:[0,1]
	v_pk_mul_f32 v[10:11], v[2:3], v[10:11]
	v_pk_mul_f32 v[2:3], v[2:3], v[4:5]
	global_store_dwordx4 v[70:71], v[8:11], off offset:-2048
	global_store_dwordx4 v[18:19], v[0:3], off offset:-2048
	global_load_dwordx4 v[0:3], v[16:17], off offset:2064
	s_nop 0
	global_load_dwordx4 v[4:7], v[16:17], off offset:2048
	v_pk_mul_f32 v[8:9], v[62:63], v[74:75] op_sel_hi:[0,1]
	v_pk_mul_f32 v[10:11], v[62:63], v[76:77] op_sel_hi:[0,1]
	v_pk_mul_f32 v[22:23], v[38:39], v[22:23] op_sel_hi:[0,1]
	s_waitcnt vmcnt(0)
	v_pk_mul_f32 v[8:9], v[8:9], v[4:5]
	v_pk_mul_f32 v[10:11], v[10:11], v[6:7]
	global_store_dwordx4 v[70:71], v[8:11], off offset:-16
	v_pk_mul_f32 v[30:31], v[44:45], v[4:5]
	v_pk_mul_f32 v[32:33], v[46:47], v[6:7]
	v_pk_mul_f32 v[10:11], v[62:63], v[54:55] op_sel_hi:[0,1]
	v_pk_mul_f32 v[8:9], v[62:63], v[50:51] op_sel_hi:[0,1]
	v_pk_mul_f32 v[8:9], v[8:9], v[0:1]
	v_pk_mul_f32 v[10:11], v[10:11], v[2:3]
	global_store_dwordx4 v[40:41], v[30:33], off offset:-16
	global_store_dwordx4 v[18:19], v[8:11], off offset:-4096
	s_nop 0
	v_pk_mul_f32 v[30:31], v[22:23], v[0:1]
	v_pk_mul_f32 v[32:33], v[26:27], v[2:3]
	v_pk_mul_f32 v[8:9], v[64:65], v[52:53] op_sel_hi:[0,1]
	global_store_dwordx4 v[48:49], v[30:33], off offset:-4096
	v_pk_mul_f32 v[26:27], v[42:43], v[28:29] op_sel_hi:[0,1]
	v_pk_mul_f32 v[22:23], v[42:43], v[24:25] op_sel_hi:[0,1]
	v_pk_mul_f32 v[30:31], v[56:57], v[4:5]
	v_pk_mul_f32 v[4:5], v[8:9], v[4:5]
	v_pk_mul_f32 v[8:9], v[64:65], v[14:15] op_sel_hi:[0,1]
	v_pk_mul_f32 v[32:33], v[58:59], v[6:7]
	v_pk_mul_f32 v[6:7], v[8:9], v[6:7]
	global_store_dwordx4 v[18:19], v[4:7], off offset:-16
	v_pk_mul_f32 v[22:23], v[22:23], v[0:1]
	v_pk_mul_f32 v[24:25], v[26:27], v[2:3]
	v_pk_mul_f32 v[4:5], v[64:65], v[60:61] op_sel_hi:[0,1]
	v_pk_mul_f32 v[6:7], v[64:65], v[12:13] op_sel_hi:[0,1]
	v_pk_mul_f32 v[0:1], v[6:7], v[0:1]
	v_pk_mul_f32 v[2:3], v[4:5], v[2:3]
	global_store_dwordx4 v[18:19], v[0:3], off
	v_lshl_add_u64 v[18:19], v[18:19], 0, s[66:67]
	global_store_dwordx4 v[48:49], v[30:33], off offset:-16
	global_store_dwordx4 v[48:49], v[22:25], off
	s_cbranch_scc0 .LBB0_300
